# v47 + hgrn_r3 two conditional 4-MFMA blocks after barrier 2: all 8 A/B fragment ds_read_b128 per block issued up front (v214-233 + block temps), counted lgkmcnt 6/4/2/0 instead of pair->lgkmcnt(0)->MF
# speedup vs baseline: 1.0086x; 1.0086x over previous
; #define LAS __attribute__((address_space(3)))
; __device__ __forceinline__ unsigned pkbf(float lo, float hi) { const f32x2_t v = {lo, hi}; const bf16x2_t b = __builtin_convertvector(v, bf16x2_t); return __builtin_bit_cast(unsigned, b); }
; #define MFMA16(a, b, c) __builtin_amdgcn_mfma_f32_16x16x32_bf16((a), (b), (c), 0, 0, 0)
; __device__ __forceinline__ void hgrn_r3(const GAS bf16* proj, const GAS float* RU, const GAS float* RD, GAS bf16* y, int TOKG, const GAS float* ogain, unsigned char* lds, int tid, int lane, int wave, int bid, int G) {
;     ...
;             __syncthreads();
;             { const int tt = wave >> 1;
; #pragma unroll
;               for (int ss2 = 0; ss2 < 2; ++ss2) { const int ss = 2 * (wave & 1) + ss2; f32x4h a = {0.f, 0.f, 0.f, 0.f};
;                   if (ss <= tt) {
; #pragma unroll
;                       for (int ks = 0; ks < 4; ++ks) { const bf16x8 kmf = *(const LAS bf16x8*)(L + H3_KM + (16 * ss + fr) * HQS + (32 * ks + 8 * fq) * 2);
;                           const bf16x8 qmf = *(const LAS bf16x8*)(L + H3_QM + (16 * tt + fr) * HQS + (32 * ks + 8 * fq) * 2); a = MFMA16(kmf, qmf, a); } }
;                   const int t = 16 * tt + fr, s0 = 16 * ss + 4 * fq;
;                   v2u w; w.x = pkbf(s0 <= t ? a[0] : 0.f, s0 + 1 <= t ? a[1] : 0.f); w.y = pkbf(s0 + 2 <= t ? a[2] : 0.f, s0 + 3 <= t ? a[3] : 0.f);
;                   *(LAS v2u*)(L + H3_AM + t * HS + s0 * 2) = w; } }
.LBB0_388:
	v_mov_b32_e32 v52, 0
	s_andn2_b64 vcc, exec, s[82:83]
	v_mov_b32_e32 v54, 0
	v_mov_b32_e32 v55, 0
	v_mov_b32_e32 v56, 0
	v_mov_b32_e32 v57, 0
	s_waitcnt lgkmcnt(0)
	s_barrier
	s_cbranch_vccnz .LBB0_390
	ds_read_b128 v[54:57], v125 offset:34816
	ds_read_b128 v[58:61], v134 offset:17408
	ds_read_b128 v[62:65], v125 offset:34880
	ds_read_b128 v[214:217], v134 offset:17472
	ds_read_b128 v[218:221], v125 offset:34944
	ds_read_b128 v[222:225], v134 offset:17536
	ds_read_b128 v[226:229], v125 offset:35008
	ds_read_b128 v[230:233], v134 offset:17600
	s_waitcnt lgkmcnt(6)
	v_mfma_f32_16x16x32_bf16 v[54:57], v[54:57], v[58:61], 0
	s_waitcnt lgkmcnt(4)
	v_mfma_f32_16x16x32_bf16 v[54:57], v[62:65], v[214:217], v[54:57]
	s_waitcnt lgkmcnt(2)
	v_mfma_f32_16x16x32_bf16 v[54:57], v[218:221], v[222:225], v[54:57]
	s_waitcnt lgkmcnt(0)
	v_mfma_f32_16x16x32_bf16 v[54:57], v[226:229], v[230:233], v[54:57]
.LBB0_390:
	s_nop 7
	v_cndmask_b32_e64 v53, v54, 0, s[22:23]
	v_cndmask_b32_e64 v54, 0, v55, s[24:25]
	v_cvt_pk_bf16_f32 v54, v53, v54
	v_cndmask_b32_e64 v53, v56, 0, s[26:27]
	v_cndmask_b32_e64 v55, v57, 0, s[28:29]
	v_cvt_pk_bf16_f32 v55, v53, v55
	ds_write_b64 v126, v[54:55]
	s_andn2_b64 vcc, exec, s[48:49]
	v_mov_b32_e32 v53, 0
	v_mov_b32_e32 v54, 0
	v_mov_b32_e32 v55, 0
	s_cbranch_vccnz .LBB0_392
	ds_read_b128 v[52:55], v127 offset:34816
	ds_read_b128 v[56:59], v134 offset:17408
	ds_read_b128 v[60:63], v127 offset:34880
	ds_read_b128 v[214:217], v134 offset:17472
	ds_read_b128 v[218:221], v127 offset:34944
	ds_read_b128 v[222:225], v134 offset:17536
	ds_read_b128 v[226:229], v127 offset:35008
	ds_read_b128 v[230:233], v134 offset:17600
	s_waitcnt lgkmcnt(6)
	v_mfma_f32_16x16x32_bf16 v[52:55], v[52:55], v[56:59], 0
	s_waitcnt lgkmcnt(4)
	v_mfma_f32_16x16x32_bf16 v[52:55], v[60:63], v[214:217], v[52:55]
	s_waitcnt lgkmcnt(2)
	v_mfma_f32_16x16x32_bf16 v[52:55], v[218:221], v[222:225], v[52:55]
	s_waitcnt lgkmcnt(0)
	v_mfma_f32_16x16x32_bf16 v[52:55], v[226:229], v[230:233], v[52:55]
